# conversion work-list rebalancing on unified zeroless stack: 5632 gate/up items of each MLA layer move from its w_in phase to the previous layer's gate/up-phase idle tail
# baseline (speedup 1.0000x reference)
.LBB0_299:
	s_abs_i32 s6, s80
	v_cvt_f32_u32_e32 v0, s6
	s_sub_i32 s7, 0, s6
	v_rcp_iflag_f32_e32 v0, v0
	s_nop 0
	v_mul_f32_e32 v0, 0x4f7ffffe, v0
	v_cvt_u32_f32_e32 v0, v0
	s_nop 0
	v_readfirstlane_b32 s8, v0
	s_mul_i32 s7, s7, s8
	s_mul_hi_u32 s7, s8, s7
	s_add_i32 s8, s8, s7
	s_mul_hi_u32 s7, s8, 0xa0
	s_mul_i32 s7, s7, s6
	s_sub_i32 s7, 0xa0, s7
	s_sub_i32 s8, s7, s6
	s_cmp_ge_u32 s7, s6
	s_cselect_b32 s7, s8, s7
	s_sub_i32 s8, s7, s6
	s_cmp_ge_u32 s7, s6
	s_cselect_b32 s6, s8, s7
	s_cmp_lt_i32 s81, s6
	s_cbranch_scc1 .LBB0_360
	s_ashr_i32 s7, s82, 6
	s_mul_i32 s8, s76, 0xab40
	s_sub_i32 s9, s81, s6
	s_add_i32 s18, s8, 0x9540
	s_lshl_b32 s9, s9, 3
	s_add_i32 s8, s8, s7
	s_add_i32 s8, s8, s9
	s_add_i32 s19, s8, 0x7f40
	s_cmp_ge_i32 s19, s18
	s_cbranch_scc1 .LBB0_360
	s_sub_i32 s6, s80, s6
	s_lshl_b32 s20, s6, 3
	s_lshl_b32 s6, s7, 14
	s_add_i32 s6, s6, 0
	s_add_u32 s21, s10, 0x10612000
	s_addc_u32 s22, s11, 0
	s_add_u32 s23, s10, 0x5612000
	s_addc_u32 s24, s11, 0
	s_add_u32 s25, s10, 0x4612000
	s_addc_u32 s26, s11, 0
	s_add_u32 s27, s10, 0x3e12000
	s_addc_u32 s28, s11, 0
	s_add_u32 s29, s10, 0x3812000
	s_addc_u32 s30, s11, 0
	s_add_u32 s31, s10, 0x1e12000
	v_bfe_u32 v10, v188, 3, 3
	s_addc_u32 s33, s11, 0
	v_lshlrev_b32_e32 v0, 2, v188
	v_and_b32_e32 v3, 7, v188
	v_lshlrev_b32_e32 v6, 2, v10
	s_add_u32 s34, s10, 0x612000
	v_and_b32_e32 v0, 28, v0
	v_lshl_add_u32 v4, v3, 4, s6
	v_mul_u32_u24_e32 v5, 0x84, v10
	v_lshlrev_b32_e32 v2, 3, v3
	v_mul_u32_u24_e32 v3, 0x420, v3
	v_and_b32_e32 v14, 16, v6
	s_addc_u32 s35, s11, 0
	v_or_b32_e32 v11, 8, v10
	v_or_b32_e32 v12, 16, v10
	v_or_b32_e32 v13, 24, v10
	v_add3_u32 v15, s6, v3, v6
	v_or_b32_e32 v16, 4, v14
	v_or_b32_e32 v17, 8, v14
	v_or_b32_e32 v18, 12, v6
	v_lshlrev_b32_e32 v0, 2, v0
	v_add_u32_e32 v19, v4, v5
	v_lshlrev_b32_e32 v6, 1, v2
	s_mov_b32 s99, 0
	s_branch .LBB0_304

.LBB0_1067:
	s_abs_i32 s4, s36
	v_cvt_f32_u32_e32 v0, s4
	s_sub_i32 s5, 0, s4
	v_rcp_iflag_f32_e32 v0, v0
	s_nop 0
	v_mul_f32_e32 v0, 0x4f7ffffe, v0
	v_cvt_u32_f32_e32 v0, v0
	s_nop 0
	v_readfirstlane_b32 s8, v0
	s_mul_i32 s5, s5, s8
	s_mul_hi_u32 s5, s8, s5
	s_add_i32 s8, s8, s5
	s_mul_hi_u32 s5, s8, 0x580
	s_mul_i32 s5, s5, s4
	s_sub_i32 s5, 0x580, s5
	s_sub_i32 s8, s5, s4
	s_cmp_ge_u32 s5, s4
	s_cselect_b32 s5, s8, s5
	s_sub_i32 s8, s5, s4
	s_cmp_ge_u32 s5, s4
	s_cselect_b32 s4, s8, s5
	s_cmp_lt_i32 s37, s4
	s_cbranch_scc1 .LBB0_1128
	s_ashr_i32 s5, s38, 6
	s_and_b64 s[8:9], s[74:75], exec
	s_waitcnt lgkmcnt(0)
	s_cselect_b32 s11, s90, 0x1340
	s_add_i32 s8, s56, 1
	s_lshr_b32 s9, s8, 1
	s_bitcmp1_b32 s8, 0
	s_mul_i32 s9, s9, 0xab40
	s_cselect_b32 s8, 0x5600, 0
	s_add_i32 s14, s9, s8
	s_and_b64 s[8:9], s[74:75], exec
	s_cselect_b32 s8, 0x2940, s90
	s_add_i32 s14, s14, s8
	s_cmp_eq_u32 s57, 1
	s_mov_b32 s8, 0x8200
	s_mul_i32 s10, s76, 0xab40
	s_cselect_b32 s8, s8, 0x2c00
	s_add_i32 s8, s8, s10
	s_add_i32 s8, s8, s11
	s_add_i32 s8, s8, s5
	s_cmp_lg_u32 s56, 3
	s_cselect_b32 s16, s14, 0x15680
	s_sub_i32 s9, s37, s4
	s_lshl_b32 s9, s9, 3
	s_add_i32 s17, s8, s9
	s_cmp_ge_i32 s17, s16
	s_cbranch_scc1 .LBB0_1128
	s_sub_i32 s4, s36, s4
	s_lshl_b32 s18, s4, 3
	s_lshl_b32 s4, s5, 14
	s_add_i32 s4, s4, 0
	s_add_u32 s19, s6, 0x10612000
	s_addc_u32 s20, s7, 0
	s_add_u32 s21, s6, 0x4612000
	s_addc_u32 s22, s7, 0
	s_add_u32 s23, s6, 0x3e12000
	s_addc_u32 s24, s7, 0
	s_add_u32 s25, s6, 0x3812000
	s_addc_u32 s26, s7, 0
	s_add_u32 s27, s6, 0x2e12000
	s_addc_u32 s28, s7, 0
	s_add_u32 s29, s6, 0x1e12000
	v_bfe_u32 v10, v136, 3, 3
	s_addc_u32 s30, s7, 0
	v_lshlrev_b32_e32 v0, 2, v136
	v_and_b32_e32 v3, 7, v136
	v_lshlrev_b32_e32 v6, 2, v10
	s_add_u32 s31, s6, 0x612000
	v_and_b32_e32 v0, 28, v0
	v_lshl_add_u32 v4, v3, 4, s4
	v_mul_u32_u24_e32 v5, 0x84, v10
	v_lshlrev_b32_e32 v2, 3, v3
	v_mul_u32_u24_e32 v3, 0x420, v3
	v_and_b32_e32 v14, 16, v6
	s_addc_u32 s33, s7, 0
	v_or_b32_e32 v11, 8, v10
	v_or_b32_e32 v12, 16, v10
	v_or_b32_e32 v13, 24, v10
	v_add3_u32 v15, s4, v3, v6
	v_or_b32_e32 v16, 4, v14
	v_or_b32_e32 v17, 8, v14
	v_or_b32_e32 v18, 12, v6
	v_lshlrev_b32_e32 v0, 2, v0
	v_add_u32_e32 v19, v4, v5
	v_lshlrev_b32_e32 v6, 1, v2
	s_mov_b32 s99, 0
	s_branch .LBB0_1072
